# code placement: hot loop heads at 64-byte boundary plus 4 bytes
# speedup vs baseline: 1.0031x; 1.0031x over previous
.Lfw_0:
	.p2align 6
	s_nop 0

.LBB0_716:
	s_or_b64 exec, exec, s[8:9]
	s_waitcnt vmcnt(4)
	v_mul_u32_u24_e32 v0, 0xd0, v33
	v_add3_u32 v227, 0, v0, v196
	s_waitcnt lgkmcnt(0)
	s_barrier
	ds_read_b128 v[0:3], v227
	s_waitcnt vmcnt(1)
	ds_read_b128 v[4:7], v227 offset:32
	s_waitcnt vmcnt(0) lgkmcnt(1)
	v_mfma_f32_32x32x16_bf16 v[16:31], v[0:3], v[112:115], 0
	ds_read_b128 v[0:3], v227 offset:6656
	ds_read_b128 v[8:11], v227 offset:6688
	v_lshlrev_b32_e32 v228, 2, v32
	v_or_b32_e32 v229, s12, v33
	s_and_b32 s7, s1, 7
	s_lshl_b32 s36, s7, 7
	s_lshl_b32 s7, s11, 2
	s_mov_b32 s60, 0
	s_waitcnt lgkmcnt(1)
	v_mfma_f32_32x32x16_bf16 v[34:49], v[0:3], v[112:115], 0
	s_movk_i32 s8, 0xc0
	s_lshl_b32 s11, s2, 8
	s_mov_b32 s61, s60
	s_mov_b32 s62, s60
	s_mov_b32 s63, s60
	s_mov_b32 s64, s60
	s_mov_b32 s65, s60
	v_mfma_f32_32x32x16_bf16 v[16:31], v[4:7], v[116:119], v[16:31]
	ds_read_b128 v[0:3], v227 offset:64
	ds_read_b128 v[4:7], v227 offset:96
	s_mov_b32 s66, s60
	s_mov_b32 s67, s60
	s_mov_b32 s68, s60
	s_mov_b32 s69, s60
	s_mov_b32 s70, s60
	s_mov_b32 s71, s60
	s_waitcnt lgkmcnt(2)
	v_mfma_f32_32x32x16_bf16 v[34:49], v[8:11], v[116:119], v[34:49]
	s_mov_b32 s72, s60
	s_mov_b32 s73, s60
	s_mov_b32 s74, s60
	s_mov_b32 s75, s60
	v_mov_b32_e32 v138, v197
	v_mov_b32_e32 v139, v197
	v_mov_b32_e32 v136, v197
	s_waitcnt lgkmcnt(1)
	v_mfma_f32_32x32x16_bf16 v[16:31], v[0:3], v[120:123], v[16:31]
	ds_read_b128 v[0:3], v227 offset:6720
	ds_read_b128 v[8:11], v227 offset:6752
	v_mov_b32_e32 v137, v197
	v_mov_b64_e32 v[154:155], v[138:139]
	v_ashrrev_i32_e32 v205, 31, v204
	s_add_i32 s15, s7, 4
	v_add_u32_e32 v231, 0, v51
	v_lshlrev_b32_e32 v212, 2, v54
	s_waitcnt lgkmcnt(1)
	v_mfma_f32_32x32x16_bf16 v[34:49], v[0:3], v[120:123], v[34:49]
	ds_read_b128 v[0:3], v227 offset:128
	v_mov_b32_e32 v213, v197
	v_lshlrev_b32_e32 v214, 3, v52
	v_mov_b32_e32 v215, v197
	v_lshlrev_b32_e32 v216, 2, v52
	v_mov_b32_e32 v217, v197
	v_mul_hi_u32_u24_e32 v219, 6, v54
	v_mfma_f32_32x32x16_bf16 v[16:31], v[4:7], v[124:127], v[16:31]
	v_lshrrev_b32_e32 v4, 2, v50
	v_and_or_b32 v33, v4, 3, v228
	v_lshlrev_b32_e32 v4, 1, v50
	v_and_b32_e32 v53, 32, v4
	v_lshlrev_b32_e32 v4, 3, v50
	v_and_b32_e32 v55, 24, v4
	v_mul_u32_u24_e32 v218, 6, v54
	s_waitcnt lgkmcnt(1)
	v_mfma_f32_32x32x16_bf16 v[34:49], v[8:11], v[124:127], v[34:49]
	ds_read_b128 v[4:7], v227 offset:6784
	ds_read_b128 v[8:11], v227 offset:160
	ds_read_b128 v[58:61], v227 offset:6816
	v_mul_hi_u32_u24_e32 v221, 6, v52
	v_mul_u32_u24_e32 v220, 6, v52
	v_mov_b32_e32 v234, 0
	v_mov_b64_e32 v[152:153], v[136:137]
	s_waitcnt lgkmcnt(0)
	v_mfma_f32_32x32x16_bf16 v[16:31], v[0:3], v[128:131], v[16:31]
	s_barrier
	v_mfma_f32_32x32x16_bf16 v[34:49], v[4:7], v[128:131], v[34:49]
	v_mfma_f32_32x32x16_bf16 v[16:31], v[8:11], v[132:135], v[16:31]
	v_mov_b64_e32 v[0:1], s[60:61]
	v_mov_b64_e32 v[14:15], s[74:75]
	v_mov_b64_e32 v[2:3], s[62:63]
	v_mov_b64_e32 v[4:5], s[64:65]
	v_mov_b64_e32 v[6:7], s[66:67]
	v_mov_b64_e32 v[8:9], s[68:69]
	v_mov_b64_e32 v[10:11], s[70:71]
	v_mfma_f32_32x32x16_bf16 v[34:49], v[58:61], v[132:135], v[34:49]
	s_nop 3
	v_max_f32_e32 v32, v17, v17
	v_max_f32_e32 v62, v16, v16
	v_max_f32_e32 v32, v62, v32
	v_mov_b64_e32 v[12:13], s[72:73]
	s_nop 3
	v_max3_f32 v58, v18, v19, v35
	v_max3_f32 v32, v32, v34, v36
	v_max3_f32 v32, v32, v37, v20
	v_max3_f32 v58, v58, v22, v23
	v_max3_f32 v32, v32, v21, v38
	v_max3_f32 v58, v58, v40, v41
	v_max3_f32 v32, v32, v39, v24
	v_max3_f32 v58, v58, v26, v27
	v_max3_f32 v32, v32, v25, v42
	v_max3_f32 v58, v58, v44, v45
	v_max3_f32 v32, v32, v43, v28
	v_max3_f32 v58, v58, v30, v31
	v_max3_f32 v32, v32, v29, v46
	v_max3_f32 v58, v58, v48, v49
	v_max3_f32 v32, v32, v47, v58
	v_mov_b32_e32 v58, v32
	s_nop 1
	v_permlane32_swap_b32_e32 v32, v58
	v_max_f32_e32 v58, v58, v58
	v_max_f32_e32 v32, v32, v32
	v_max_f32_e32 v230, v32, v58
	v_sub_f32_e32 v66, v18, v230
	v_sub_f32_e32 v64, v16, v230
	v_mad_u32_u24 v16, v33, s8, 0
	s_add_i32 s8, s11, 0xffffc140
	v_and_b32_e32 v18, 7, v50
	v_sub_f32_e32 v65, v17, v230
	v_add3_u32 v232, v16, v53, v55
	v_or_b32_e32 v233, s8, v228
	v_lshl_add_u64 v[16:17], v[56:57], 0, s[36:37]
	v_lshlrev_b32_e32 v196, 4, v18
	v_readlane_b32 s8, v250, 20
	v_lshl_add_u64 v[16:17], v[16:17], 0, v[196:197]
	v_readlane_b32 s9, v250, 21
	v_xor_b32_e32 v32, 0x80000000, v230
	v_sub_f32_e32 v79, v31, v230
	v_sub_f32_e32 v78, v30, v230
	v_sub_f32_e32 v77, v29, v230
	v_sub_f32_e32 v76, v28, v230
	v_sub_f32_e32 v75, v27, v230
	v_sub_f32_e32 v74, v26, v230
	v_sub_f32_e32 v73, v25, v230
	v_sub_f32_e32 v72, v24, v230
	v_sub_f32_e32 v71, v23, v230
	v_sub_f32_e32 v70, v22, v230
	v_sub_f32_e32 v69, v21, v230
	v_sub_f32_e32 v68, v20, v230
	v_sub_f32_e32 v67, v19, v230
	v_lshl_add_u64 v[210:211], s[8:9], 0, v[16:17]
	v_mov_b64_e32 v[30:31], v[14:15]
	v_sub_f32_e32 v111, v49, v230
	v_sub_f32_e32 v110, v48, v230
	v_sub_f32_e32 v109, v47, v230
	v_sub_f32_e32 v108, v46, v230
	v_sub_f32_e32 v107, v45, v230
	v_sub_f32_e32 v106, v44, v230
	v_sub_f32_e32 v105, v43, v230
	v_sub_f32_e32 v104, v42, v230
	v_sub_f32_e32 v103, v41, v230
	v_sub_f32_e32 v102, v40, v230
	v_sub_f32_e32 v101, v39, v230
	v_sub_f32_e32 v100, v38, v230
	v_sub_f32_e32 v99, v37, v230
	v_sub_f32_e32 v98, v36, v230
	v_sub_f32_e32 v97, v35, v230
	v_sub_f32_e32 v96, v34, v230
	v_lshlrev_b32_e32 v196, 3, v54
	v_mov_b32_e32 v48, 0
	v_mov_b64_e32 v[28:29], v[12:13]
	v_mov_b64_e32 v[26:27], v[10:11]
	v_mov_b64_e32 v[24:25], v[8:9]
	v_mov_b64_e32 v[22:23], v[6:7]
	v_mov_b64_e32 v[20:21], v[4:5]
	v_mov_b64_e32 v[18:19], v[2:3]
	v_mov_b64_e32 v[16:17], v[0:1]
	v_mov_b32_e32 v33, v32
	v_mov_b32_e32 v34, v32
	v_mov_b32_e32 v35, v32
	v_mov_b32_e32 v36, v32
	v_mov_b32_e32 v37, v32
	v_mov_b32_e32 v38, v32
	v_mov_b32_e32 v39, v32
	v_mov_b32_e32 v40, v32
	v_mov_b32_e32 v41, v32
	v_mov_b32_e32 v42, v32
	v_mov_b32_e32 v43, v32
	v_mov_b32_e32 v44, v32
	v_mov_b32_e32 v45, v32
	v_mov_b32_e32 v46, v32
	v_mov_b32_e32 v47, v32
	.p2align 6
	s_nop 0

.LBB0_762:
	s_nop 7
	v_max_f32_e32 v32, v1, v1
	v_max_f32_e32 v33, v0, v0
	v_max_f32_e32 v32, v33, v32
	v_max3_f32 v33, v2, v3, v17
	v_max3_f32 v32, v32, v16, v18
	v_max3_f32 v32, v32, v19, v4
	v_max3_f32 v33, v33, v6, v7
	v_max3_f32 v32, v32, v5, v20
	v_max3_f32 v33, v33, v22, v23
	v_max3_f32 v32, v32, v21, v8
	v_max3_f32 v33, v33, v10, v11
	v_max3_f32 v32, v32, v9, v24
	v_max3_f32 v33, v33, v26, v27
	v_max3_f32 v32, v32, v25, v12
	v_max3_f32 v33, v33, v14, v15
	v_max3_f32 v32, v32, v13, v28
	v_max3_f32 v33, v33, v30, v31
	v_max3_f32 v32, v32, v29, v33
	v_mov_b32_e32 v33, v32
	s_nop 1
	v_permlane32_swap_b32_e32 v32, v33
	s_cmp_lt_i32 s2, 0
	s_barrier
	s_cbranch_scc1 .LBB0_702
	v_lshrrev_b32_e32 v35, 2, v34
	v_max_f32_e32 v32, v32, v32
	v_max_f32_e32 v33, v33, v33
	v_and_or_b32 v35, v35, 3, v226
	v_lshlrev_b32_e32 v37, 1, v34
	v_lshlrev_b32_e32 v39, 3, v34
	v_max_f32_e32 v230, v32, v33
	s_movk_i32 s8, 0xc0
	v_and_b32_e32 v37, 32, v37
	v_and_b32_e32 v39, 24, v39
	v_sub_f32_e32 v64, v0, v230
	v_mad_u32_u24 v0, v35, s8, 0
	v_sub_f32_e32 v66, v2, v230
	v_add3_u32 v231, v0, v37, v39
	v_subrev_u32_e32 v0, s11, v226
	v_and_b32_e32 v2, 7, v34
	v_sub_f32_e32 v65, v1, v230
	v_add_u32_e32 v232, 0x60, v0
	v_lshl_add_u64 v[0:1], v[40:41], 0, s[36:37]
	v_lshlrev_b32_e32 v196, 4, v2
	v_readlane_b32 s8, v250, 20
	v_sub_f32_e32 v79, v15, v230
	v_sub_f32_e32 v78, v14, v230
	v_lshl_add_u64 v[0:1], v[0:1], 0, v[196:197]
	v_readlane_b32 s9, v250, 21
	v_mov_b32_e32 v14, v197
	v_mov_b32_e32 v15, v197
	v_mov_b32_e32 v138, v197
	v_mov_b32_e32 v139, v197
	s_lshl_b32 s2, s2, 2
	v_xor_b32_e32 v32, 0x80000000, v230
	v_sub_f32_e32 v111, v31, v230
	v_sub_f32_e32 v110, v30, v230
	v_sub_f32_e32 v109, v29, v230
	v_sub_f32_e32 v108, v28, v230
	v_sub_f32_e32 v107, v27, v230
	v_sub_f32_e32 v106, v26, v230
	v_sub_f32_e32 v105, v25, v230
	v_sub_f32_e32 v104, v24, v230
	v_sub_f32_e32 v103, v23, v230
	v_sub_f32_e32 v102, v22, v230
	v_sub_f32_e32 v101, v21, v230
	v_sub_f32_e32 v100, v20, v230
	v_sub_f32_e32 v99, v19, v230
	v_sub_f32_e32 v98, v18, v230
	v_sub_f32_e32 v97, v17, v230
	v_sub_f32_e32 v96, v16, v230
	v_sub_f32_e32 v77, v13, v230
	v_sub_f32_e32 v76, v12, v230
	v_sub_f32_e32 v75, v11, v230
	v_sub_f32_e32 v74, v10, v230
	v_sub_f32_e32 v73, v9, v230
	v_sub_f32_e32 v72, v8, v230
	v_sub_f32_e32 v71, v7, v230
	v_sub_f32_e32 v70, v6, v230
	v_sub_f32_e32 v69, v5, v230
	v_sub_f32_e32 v68, v4, v230
	v_sub_f32_e32 v67, v3, v230
	v_lshl_add_u64 v[210:211], s[8:9], 0, v[0:1]
	v_mov_b32_e32 v0, v197
	v_mov_b32_e32 v1, v197
	v_mov_b32_e32 v2, v197
	v_mov_b32_e32 v3, v197
	v_mov_b32_e32 v4, v197
	v_mov_b32_e32 v5, v197
	v_mov_b32_e32 v6, v197
	v_mov_b32_e32 v7, v197
	v_mov_b32_e32 v8, v197
	v_mov_b32_e32 v9, v197
	v_mov_b32_e32 v10, v197
	v_mov_b32_e32 v11, v197
	v_mov_b32_e32 v12, v197
	v_mov_b32_e32 v13, v197
	v_mov_b32_e32 v136, v197
	v_mov_b32_e32 v137, v197
	v_mov_b64_e32 v[154:155], v[138:139]
	v_mov_b64_e32 v[30:31], v[14:15]
	s_add_i32 s7, s2, 4
	v_lshlrev_b32_e32 v196, 3, v38
	v_lshlrev_b32_e32 v212, 2, v38
	v_mov_b32_e32 v213, v197
	v_lshlrev_b32_e32 v214, 3, v36
	v_mov_b32_e32 v215, v197
	v_lshlrev_b32_e32 v216, 2, v36
	v_mov_b32_e32 v217, v197
	v_mul_hi_u32_u24_e32 v219, 6, v38
	v_mul_u32_u24_e32 v218, 6, v38
	v_mul_hi_u32_u24_e32 v221, 6, v36
	v_mul_u32_u24_e32 v220, 6, v36
	s_mov_b32 s15, 0
	v_mov_b32_e32 v233, 0
	v_mov_b64_e32 v[152:153], v[136:137]
	v_mov_b32_e32 v48, 0
	v_mov_b64_e32 v[28:29], v[12:13]
	v_mov_b64_e32 v[26:27], v[10:11]
	v_mov_b64_e32 v[24:25], v[8:9]
	v_mov_b64_e32 v[22:23], v[6:7]
	v_mov_b64_e32 v[20:21], v[4:5]
	v_mov_b64_e32 v[18:19], v[2:3]
	v_mov_b64_e32 v[16:17], v[0:1]
	v_mov_b32_e32 v33, v32
	v_mov_b32_e32 v34, v32
	v_mov_b32_e32 v35, v32
	v_mov_b32_e32 v36, v32
	v_mov_b32_e32 v37, v32
	v_mov_b32_e32 v38, v32
	v_mov_b32_e32 v39, v32
	v_mov_b32_e32 v40, v32
	v_mov_b32_e32 v41, v32
	v_mov_b32_e32 v42, v32
	v_mov_b32_e32 v43, v32
	v_mov_b32_e32 v44, v32
	v_mov_b32_e32 v45, v32
	v_mov_b32_e32 v46, v32
	v_mov_b32_e32 v47, v32
	.p2align 6
	s_nop 0
